# rope-q fragments and first K/V tile of the selected branch loaded at the end of the compressed branch (land under the top-16 selection)
# speedup vs baseline: 1.0337x; 1.0022x over previous
; __device__ __forceinline__ void phase4_attn(const Args& a, LAS unsigned char* lds) {
;     ...
;                     ls += __shfl_xor(ls, 32);
;                     const float inv = 1.f / fmaxf(ls, 1e-20f);
; #pragma unroll
;                     for (int mt = 0; mt < 4; ++mt) s4[mt] *= inv;
;                     if (t >= 16) {
;                         float oprev = 0.f;
; #pragma unroll
;                         for (int idx = 0; idx < 16; ++idx) {
;                             const int mt = idx >> 2, ap = idx & 3;
;                             const float tail = 0.5f * s4[mt][4 * ap + 3];
;                             const float ot = __shfl_xor(tail, 32);
;                             const float inner = s4[mt][4 * ap] + s4[mt][4 * ap + 1] + s4[mt][4 * ap + 2] + tail;
;                             const float prev = h ? ot : oprev;
;                             oprev = ot;
;                             IMP[(g * 64 + ql) * A_IMPSTR + 8 * mt + 2 * ap + h] = inner + prev;
;                         }
;                     }
.Lc0_fin:
	v_add_f32_e32 v232, v232, v233
	ds_bpermute_b32 v239, v193, v232
	s_waitcnt lgkmcnt(0)
	v_add_f32_e32 v239, v232, v239
	v_max_f32_e32 v239, 0x1e3ce508, v239
	v_div_scale_f32 v240, s[44:45], v239, v239, 1.0
	v_rcp_f32_e32 v241, v240
	v_div_scale_f32 v242, vcc, 1.0, v239, 1.0
	s_nop 0
	v_fma_f32 v243, -v240, v241, 1.0
	v_fmac_f32_e32 v241, v243, v241
	v_mul_f32_e32 v243, v242, v241
	v_fma_f32 v237, -v240, v243, v242
	v_fmac_f32_e32 v243, v237, v241
	v_fma_f32 v240, -v240, v243, v242
	v_div_fmas_f32 v240, v240, v241, v243
	v_div_fixup_f32 v238, v240, v239, 1.0
	v_mul_f32_e32 v0, v0, v238
	v_mul_f32_e32 v1, v1, v238
	v_mul_f32_e32 v2, v2, v238
	v_mul_f32_e32 v3, v3, v238
	v_mul_f32_e32 v4, v4, v238
	v_mul_f32_e32 v5, v5, v238
	v_mul_f32_e32 v6, v6, v238
	v_mul_f32_e32 v7, v7, v238
	v_mul_f32_e32 v8, v8, v238
	v_mul_f32_e32 v9, v9, v238
	v_mul_f32_e32 v10, v10, v238
	v_mul_f32_e32 v11, v11, v238
	v_mul_f32_e32 v12, v12, v238
	v_mul_f32_e32 v13, v13, v238
	v_mul_f32_e32 v14, v14, v238
	v_mul_f32_e32 v15, v15, v238
	v_mul_f32_e32 v16, v16, v238
	v_mul_f32_e32 v17, v17, v238
	v_mul_f32_e32 v18, v18, v238
	v_mul_f32_e32 v19, v19, v238
	v_mul_f32_e32 v20, v20, v238
	v_mul_f32_e32 v21, v21, v238
	v_mul_f32_e32 v22, v22, v238
	v_mul_f32_e32 v23, v23, v238
	v_mul_f32_e32 v24, v24, v238
	v_mul_f32_e32 v25, v25, v238
	v_mul_f32_e32 v26, v26, v238
	v_mul_f32_e32 v27, v27, v238
	v_mul_f32_e32 v28, v28, v238
	v_mul_f32_e32 v29, v29, v238
	v_mul_f32_e32 v30, v30, v238
	v_mul_f32_e32 v31, v31, v238
	s_cmp_gt_u32 s38, 15
	s_cbranch_scc0 .Lc0_noimp
	v_cmp_ne_u32_e64 s[46:47], 0, v101
	ds_bpermute_b32 v32, v193, v176
	ds_bpermute_b32 v33, v193, v177
	ds_bpermute_b32 v34, v193, v178
	ds_bpermute_b32 v35, v193, v179
	ds_bpermute_b32 v36, v193, v180
	ds_bpermute_b32 v37, v193, v181
	ds_bpermute_b32 v38, v193, v182
	ds_bpermute_b32 v39, v193, v183
	ds_bpermute_b32 v40, v193, v246
	ds_bpermute_b32 v41, v193, v247
	ds_bpermute_b32 v42, v193, v248
	ds_bpermute_b32 v43, v193, v249
	ds_bpermute_b32 v44, v193, v250
	ds_bpermute_b32 v45, v193, v251
	ds_bpermute_b32 v46, v193, v252
	ds_bpermute_b32 v47, v193, v253
	v_lshrrev_b32_e32 v48, 7, v152
	v_lshl_or_b32 v48, v48, 6, v98
	v_mul_u32_u24_e32 v48, 0x84, v48
	v_add_u32_e32 v48, v48, v155
	v_add_u32_e32 v48, 0x19e00, v48
	s_waitcnt lgkmcnt(0)
	v_cndmask_b32_e64 v49, 0, v32, s[46:47]
	v_add_f32_e32 v49, v160, v49
	v_mul_f32_e32 v49, v49, v238
	ds_write_b32 v48, v49 offset:0
	v_cndmask_b32_e64 v50, v32, v33, s[46:47]
	v_add_f32_e32 v50, v161, v50
	v_mul_f32_e32 v50, v50, v238
	ds_write_b32 v48, v50 offset:8
	v_cndmask_b32_e64 v49, v33, v34, s[46:47]
	v_add_f32_e32 v49, v162, v49
	v_mul_f32_e32 v49, v49, v238
	ds_write_b32 v48, v49 offset:16
	v_cndmask_b32_e64 v50, v34, v35, s[46:47]
	v_add_f32_e32 v50, v163, v50
	v_mul_f32_e32 v50, v50, v238
	ds_write_b32 v48, v50 offset:24
	v_cndmask_b32_e64 v49, v35, v36, s[46:47]
	v_add_f32_e32 v49, v164, v49
	v_mul_f32_e32 v49, v49, v238
	ds_write_b32 v48, v49 offset:32
	v_cndmask_b32_e64 v50, v36, v37, s[46:47]
	v_add_f32_e32 v50, v165, v50
	v_mul_f32_e32 v50, v50, v238
	ds_write_b32 v48, v50 offset:40
	v_cndmask_b32_e64 v49, v37, v38, s[46:47]
	v_add_f32_e32 v49, v166, v49
	v_mul_f32_e32 v49, v49, v238
	ds_write_b32 v48, v49 offset:48
	v_cndmask_b32_e64 v50, v38, v39, s[46:47]
	v_add_f32_e32 v50, v167, v50
	v_mul_f32_e32 v50, v50, v238
	ds_write_b32 v48, v50 offset:56
	v_cndmask_b32_e64 v49, v39, v40, s[46:47]
	v_add_f32_e32 v49, v168, v49
	v_mul_f32_e32 v49, v49, v238
	ds_write_b32 v48, v49 offset:64
	v_cndmask_b32_e64 v50, v40, v41, s[46:47]
	v_add_f32_e32 v50, v169, v50
	v_mul_f32_e32 v50, v50, v238
	ds_write_b32 v48, v50 offset:72
	v_cndmask_b32_e64 v49, v41, v42, s[46:47]
	v_add_f32_e32 v49, v170, v49
	v_mul_f32_e32 v49, v49, v238
	ds_write_b32 v48, v49 offset:80
	v_cndmask_b32_e64 v50, v42, v43, s[46:47]
	v_add_f32_e32 v50, v171, v50
	v_mul_f32_e32 v50, v50, v238
	ds_write_b32 v48, v50 offset:88
	v_cndmask_b32_e64 v49, v43, v44, s[46:47]
	v_add_f32_e32 v49, v172, v49
	v_mul_f32_e32 v49, v49, v238
	ds_write_b32 v48, v49 offset:96
	v_cndmask_b32_e64 v50, v44, v45, s[46:47]
	v_add_f32_e32 v50, v173, v50
	v_mul_f32_e32 v50, v50, v238
	ds_write_b32 v48, v50 offset:104
	v_cndmask_b32_e64 v49, v45, v46, s[46:47]
	v_add_f32_e32 v49, v174, v49
	v_mul_f32_e32 v49, v49, v238
	ds_write_b32 v48, v49 offset:112
	v_cndmask_b32_e64 v50, v46, v47, s[46:47]
	v_add_f32_e32 v50, v175, v50
	v_mul_f32_e32 v50, v50, v238
	ds_write_b32 v48, v50 offset:120
; #define LAS __attribute__((address_space(3)))
; __device__ __forceinline__ void phase4_attn(const Args& a, LAS unsigned char* lds) {
;     ...
;                     const int qloc = tid >> 3, jg = tid & 7;
;                     unsigned bits = 0u;
;                     float xe[4]; int cnt[4];
; #pragma unroll
;                     for (int e = 0; e < 4; ++e) { const int j = 4 * jg + e; const LAS float* ip = IMP + qloc * A_IMPSTR + j;
;                         float x = (ip[0] + ip[64 * A_IMPSTR]) + (ip[128 * A_IMPSTR] + ip[192 * A_IMPSTR]);
;                         if (j == 0 || j == t || j == t - 1) x = 1e9f;
;                         if (j > t) x = -INFINITY;
;                         xe[e] = x; cnt[e] = 0; }
; #pragma unroll 4
;                     for (int i = 0; i < 32; ++i) { const LAS float* ip = IMP + qloc * A_IMPSTR + i;
;                         float vi = (ip[0] + ip[64 * A_IMPSTR]) + (ip[128 * A_IMPSTR] + ip[192 * A_IMPSTR]);
;                         if (i == 0 || i == t || i == t - 1) vi = 1e9f;
;                         if (i > t) vi = -INFINITY;
; #pragma unroll
;                         for (int e = 0; e < 4; ++e) cnt[e] += (vi > xe[e] || (vi == xe[e] && i < 4 * jg + e)) ? 1 : 0; }
; #pragma unroll
;                     for (int e = 0; e < 4; ++e) if (cnt[e] < 16 && xe[e] > -INFINITY) bits |= 1u << (4 * jg + e);
;     ...
;                 for (int ks = 0; ks < 4; ++ks) qf[ks] = __builtin_nontemporal_load((const bf16x8_t*)(qr + (size_t)tok * 512 + head * 64 + 16 * ks + 8 * h));
;                 const int kt_lo = t >= 8 ? t - 8 : 0, wlo = kt_lo >> 1, n_sel = (t >> 1) + 1, n_all = n_sel + ((t >> 1) - wlo + 1);
;                 const bf16_t* Ks = ksl + (size_t)bh * 2048 * 64; const bf16_t* Vs = vslT + (size_t)bh * 64 * 2048;
;                 const bf16_t* Kw = kwn + (size_t)bh * 2048 * 64; const bf16_t* Vw = vwnT + (size_t)bh * 64 * 2048;
.Lc0_noimp:
	s_waitcnt lgkmcnt(0)
	v_readlane_b32 s10, v254, 55
	v_readlane_b32 s11, v254, 56
	v_lshlrev_b32_e32 v200, 1, v156
	v_mov_b32_e32 v201, 0
	v_lshl_add_u64 v[202:203], s[10:11], 0, v[72:73]
	v_lshl_add_u64 v[202:203], v[202:203], 0, v[200:201]
	global_load_dwordx4 v[80:83], v[202:203], off nt
	global_load_dwordx4 v[84:87], v[202:203], off offset:32 nt
	global_load_dwordx4 v[88:91], v[202:203], off offset:64 nt
	global_load_dwordx4 v[92:95], v[202:203], off offset:96 nt
	v_mov_b32_e32 v200, v152
	v_lshlrev_b64 v[200:201], 4, v[200:201]
	v_lshl_add_u64 v[206:207], v[200:201], 0, s[40:41]
	v_readlane_b32 s10, v254, 41
	v_readlane_b32 s11, v254, 42
	s_nop 1
	v_lshl_add_u64 v[204:205], s[10:11], 0, v[200:201]
	global_load_dwordx4 v[208:211], v[204:205], off
	v_lshl_add_u64 v[204:205], s[10:11], 0, v[206:207]
	global_load_dwordx4 v[212:215], v[204:205], off
	v_readlane_b32 s10, v254, 33
	v_readlane_b32 s11, v254, 34
	s_nop 1
	v_lshl_add_u64 v[204:205], s[10:11], 0, v[200:201]
	global_load_dwordx4 v[104:107], v[204:205], off
	v_lshl_add_u64 v[204:205], s[10:11], 0, v[206:207]
	global_load_dwordx4 v[108:111], v[204:205], off
	s_lshl_b32 s30, 2, s38
	s_add_i32 s30, s30, -1
	s_add_i32 s80, s38, -1
	v_mov_b32_e32 v158, s30
	s_cmp_gt_u32 s38, 15
	s_cselect_b64 s[2:3], 0, -1
	s_andn2_b64 vcc, exec, s[0:1]
	s_cbranch_vccnz .LBB0_725
	s_movk_i32 s0, 0x84
	v_mul_lo_u32 v50, v99, s0
	v_readlane_b32 s0, v254, 28
	v_and_b32_e32 v33, 7, v152
	s_nop 0
	v_add_u32_e32 v46, s0, v50
	v_lshl_add_u32 v32, v33, 4, v46
	v_add_u32_e32 v40, 0x2100, v32
	v_add_u32_e32 v36, 0x4200, v32
	v_add_u32_e32 v38, 0x6300, v32
	s_barrier
	ds_read2_b32 v[34:35], v32 offset1:1
	ds_read2_b32 v[36:37], v36 offset1:1
	ds_read2_b32 v[38:39], v38 offset1:1
	ds_read2_b32 v[40:41], v40 offset1:1
	v_lshlrev_b32_e32 v32, 2, v33
	s_waitcnt lgkmcnt(3)
	v_mov_b32_e32 v42, v34
	s_waitcnt lgkmcnt(2)
	v_mov_b32_e32 v43, v36
	s_waitcnt lgkmcnt(1)
	v_mov_b32_e32 v45, v38
	s_waitcnt lgkmcnt(0)
	v_mov_b32_e32 v44, v40
	v_cmp_eq_u32_e32 vcc, 0, v33
	v_cmp_eq_u32_e64 s[0:1], s38, v32
	v_pk_add_f32 v[42:43], v[42:43], v[44:45]
	s_or_b64 s[4:5], vcc, s[0:1]
	v_cmp_eq_u32_e64 s[0:1], s80, v32
	v_add_f32_e32 v34, v42, v43
	s_or_b64 s[0:1], s[4:5], s[0:1]
	v_cndmask_b32_e64 v33, v34, v190, s[0:1]
	v_cmp_ge_u32_e64 s[0:1], s38, v32
	v_mov_b32_e32 v36, v35
	v_mov_b32_e32 v38, v41
	v_cndmask_b32_e64 v34, v191, v33, s[0:1]
	v_or_b32_e32 v33, 1, v32
	v_pk_add_f32 v[36:37], v[36:37], v[38:39]
	v_cmp_eq_u32_e64 s[0:1], s38, v33
	v_cmp_eq_u32_e64 s[4:5], s80, v33
	v_add_f32_e32 v35, v36, v37
	s_or_b64 s[0:1], s[0:1], s[4:5]
	v_or_b32_e32 v38, 2, v32
	v_cndmask_b32_e64 v33, v35, v190, s[0:1]
	v_lshl_add_u32 v35, v38, 2, v46
	v_add_u32_e32 v36, 0x2100, v35
	v_add_u32_e32 v37, 0x4200, v35
	v_add_u32_e32 v39, 0x6300, v35
	ds_read2_b32 v[40:41], v35 offset1:1
	ds_read2_b32 v[44:45], v36 offset1:1
	ds_read2_b32 v[46:47], v37 offset1:1
	ds_read2_b32 v[48:49], v39 offset1:1
	v_cmp_gt_u32_e64 s[0:1], s38, v32
	v_or_b32_e32 v42, 3, v32
	s_waitcnt lgkmcnt(2)
	v_pk_add_f32 v[40:41], v[40:41], v[44:45]
	v_cndmask_b32_e64 v36, v191, v33, s[0:1]
	s_waitcnt lgkmcnt(0)
	v_pk_add_f32 v[44:45], v[46:47], v[48:49]
	v_cmp_eq_u32_e64 s[0:1], s38, v38
	v_cmp_eq_u32_e64 s[6:7], s80, v38
	v_pk_add_f32 v[40:41], v[40:41], v[44:45]
	v_cmp_eq_u32_e64 s[4:5], s38, v42
	v_cmp_eq_u32_e64 s[8:9], s80, v42
	s_or_b64 s[0:1], s[0:1], s[6:7]
	v_cndmask_b32_e64 v37, v40, v190, s[0:1]
	s_or_b64 s[0:1], s[4:5], s[8:9]
	v_cndmask_b32_e64 v33, v41, v190, s[0:1]
	v_cmp_ge_u32_e64 s[0:1], s38, v42
	s_mov_b32 s31, 0
	s_mov_b32 s42, 1
	v_cndmask_b32_e64 v33, v191, v33, s[0:1]
	v_cmp_ge_u32_e64 s[0:1], s38, v38
	v_mov_b32_e32 v35, v32
	s_mov_b32 s43, s38
	v_cndmask_b32_e64 v40, v191, v37, s[0:1]
	s_mov_b32 s44, s80
	v_mov_b32_e32 v37, v34
	v_mov_b32_e32 v39, v36
	v_mov_b32_e32 v41, v38
	v_mov_b32_e32 v44, v40
	v_mov_b32_e32 v43, v40
	v_mov_b32_e32 v45, v42
	v_mov_b32_e32 v46, v33
	v_mov_b32_e32 v47, v33
	v_add_u32_e32 v48, 0, v50
	v_mov_b32_e32 v49, 0
	v_mov_b32_e32 v50, 0
	v_mov_b32_e32 v51, 0
	v_mov_b32_e32 v52, 0
	v_mov_b32_e32 v53, 0
	v_mov_b32_e32 v54, 0
	v_mov_b32_e32 v55, 0
	v_mov_b32_e32 v56, 0
	s_mov_b32 s45, 0

; __device__ __forceinline__ void phase4_attn(const Args& a, LAS unsigned char* lds) {
;     ...
;                     comb[hkv][0] += oc[0] * g0; comb[hkv][1] += oc[1] * g0;
;     ...
;                 const int kt_lo = t >= 8 ? t - 8 : 0, wlo = kt_lo >> 1, n_sel = (t >> 1) + 1, n_all = n_sel + ((t >> 1) - wlo + 1);
;                 const bf16_t* Ks = ksl + (size_t)bh * 2048 * 64; const bf16_t* Vs = vslT + (size_t)bh * 64 * 2048;
;                 const bf16_t* Kw = kwn + (size_t)bh * 2048 * 64; const bf16_t* Vw = vwnT + (size_t)bh * 64 * 2048;
;     ...
;                 u32x4 kR0, kR1, vR0, vR1;
;                 A_ISSUE(0);
;                 A_STAGE(0);
;                 __syncthreads();
;                 f32x16 oacc[2]; oacc[0] = zero16(); oacc[1] = zero16();
.LBB0_725:
	s_add_i32 s88, s38, -8
	s_xor_b64 s[12:13], s[64:65], -1
	s_ashr_i32 s0, s88, 1
	s_cmp_gt_u32 s38, 7
	s_cselect_b32 s31, s0, 0
	s_lshr_b32 s89, s38, 1
	s_sub_i32 s0, s89, s31
	s_add_i32 s90, s89, s0
	v_pk_fma_f32 v[148:149], v[112:113], v[0:1], 0 op_sel_hi:[0,1,0]
	v_pk_fma_f32 v[150:151], v[112:113], v[2:3], 0 op_sel_hi:[0,1,0]
	v_pk_fma_f32 v[146:147], v[112:113], v[4:5], 0 op_sel_hi:[0,1,0]
	s_add_i32 s90, s90, 1
	s_cmp_lt_u32 s90, 0x7fffffff
	v_mov_b32_e32 v0, v152
	s_cselect_b64 s[64:65], -1, 0
	v_ashrrev_i32_e32 v1, 3, v0
	v_lshlrev_b32_e32 v0, 4, v0
	v_mul_lo_u32 v2, v1, s87
	v_and_b32_e32 v0, 0x70, v0
	v_add3_u32 v0, 0, v2, v0
	s_sub_i32 s91, s31, s89
	v_pk_fma_f32 v[132:133], v[112:113], v[14:15], 0 op_sel_hi:[0,1,0]
	v_pk_fma_f32 v[138:139], v[112:113], v[12:13], 0 op_sel_hi:[0,1,0]
	v_pk_fma_f32 v[140:141], v[112:113], v[10:11], 0 op_sel_hi:[0,1,0]
	v_pk_fma_f32 v[142:143], v[112:113], v[8:9], 0 op_sel_hi:[0,1,0]
	v_pk_fma_f32 v[144:145], v[112:113], v[6:7], 0 op_sel_hi:[0,1,0]
	v_pk_fma_f32 v[134:135], v[112:113], v[16:17], 0 op_sel_hi:[0,1,0]
	v_pk_fma_f32 v[120:121], v[112:113], v[30:31], 0 op_sel_hi:[0,1,0]
	v_pk_fma_f32 v[122:123], v[112:113], v[28:29], 0 op_sel_hi:[0,1,0]
	v_pk_fma_f32 v[124:125], v[112:113], v[26:27], 0 op_sel_hi:[0,1,0]
	v_pk_fma_f32 v[126:127], v[112:113], v[24:25], 0 op_sel_hi:[0,1,0]
	v_pk_fma_f32 v[128:129], v[112:113], v[22:23], 0 op_sel_hi:[0,1,0]
	v_pk_fma_f32 v[130:131], v[112:113], v[20:21], 0 op_sel_hi:[0,1,0]
	v_pk_fma_f32 v[136:137], v[112:113], v[18:19], 0 op_sel_hi:[0,1,0]
	s_cmp_gt_u32 s90, 0x7ffffffe
	s_waitcnt vmcnt(3)
	ds_write_b128 v0, v[208:211]
	s_waitcnt vmcnt(2)
	ds_write_b128 v0, v[212:215] offset:9216
	v_mad_u64_u32 v[0:1], s[0:1], v1, s35, v[0:1]
	v_add_u32_e32 v1, 0x9000, v0
	v_add_u32_e32 v0, 0x9080, v0
	s_waitcnt vmcnt(1)
	ds_write2_b64 v1, v[104:105], v[106:107] offset1:1
	s_waitcnt vmcnt(0)
	ds_write2_b64 v0, v[108:109], v[110:111] offset1:1
	s_waitcnt lgkmcnt(0)
	s_barrier
	s_cbranch_scc1 .LBB0_794
	s_lshl_b32 s0, s89, 1
	s_sub_i32 s42, s0, s31
	s_lshl_b32 s1, s31, 1
	v_mov_b32_e32 v112, 0
	s_mov_b32 s10, 1
	s_add_i32 s11, s42, 1
	s_add_i32 s42, s42, 2
	s_sub_i32 s43, s1, s0
	s_mov_b32 s44, 0
	v_mov_b32_e32 v0, 0
	v_mov_b32_e32 v1, v112
	v_mov_b32_e32 v2, v112
	v_mov_b32_e32 v3, v112
	v_mov_b32_e32 v4, v112
	v_mov_b32_e32 v5, v112
	v_mov_b32_e32 v6, v112
	v_mov_b32_e32 v7, v112
	v_mov_b32_e32 v8, v112
	v_mov_b32_e32 v9, v112
	v_mov_b32_e32 v10, v112
	v_mov_b32_e32 v11, v112
	v_mov_b32_e32 v12, v112
	v_mov_b32_e32 v13, v112
	v_mov_b32_e32 v14, v112
	v_mov_b32_e32 v15, v112
	v_mov_b32_e32 v16, 0
	v_mov_b32_e32 v17, v112
	v_mov_b32_e32 v18, v112
	v_mov_b32_e32 v19, v112
	v_mov_b32_e32 v20, v112
	v_mov_b32_e32 v21, v112
	v_mov_b32_e32 v22, v112
	v_mov_b32_e32 v23, v112
	v_mov_b32_e32 v24, v112
	v_mov_b32_e32 v25, v112
	v_mov_b32_e32 v26, v112
	v_mov_b32_e32 v27, v112
	v_mov_b32_e32 v28, v112
	v_mov_b32_e32 v29, v112
	v_mov_b32_e32 v30, v112
	v_mov_b32_e32 v31, v112

; __device__ __forceinline__ void phase4_attn(const Args& a, LAS unsigned char* lds) {
;     ...
;                     ls += __shfl_xor(ls, 32);
;                     const float inv = 1.f / fmaxf(ls, 1e-20f);
; #pragma unroll
;                     for (int mt = 0; mt < 4; ++mt) s4[mt] *= inv;
;                     if (t >= 16) {
;                         float oprev = 0.f;
; #pragma unroll
;                         for (int idx = 0; idx < 16; ++idx) {
;                             const int mt = idx >> 2, ap = idx & 3;
;                             const float tail = 0.5f * s4[mt][4 * ap + 3];
;                             const float ot = __shfl_xor(tail, 32);
;                             const float inner = s4[mt][4 * ap] + s4[mt][4 * ap + 1] + s4[mt][4 * ap + 2] + tail;
;                             const float prev = h ? ot : oprev;
;                             oprev = ot;
;                             IMP[(g * 64 + ql) * A_IMPSTR + 8 * mt + 2 * ap + h] = inner + prev;
;                         }
;                     }
.Lc1_fin:
	v_add_f32_e32 v232, v232, v233
	ds_bpermute_b32 v239, v193, v232
	s_waitcnt lgkmcnt(0)
	v_add_f32_e32 v239, v232, v239
	v_max_f32_e32 v239, 0x1e3ce508, v239
	v_div_scale_f32 v240, s[44:45], v239, v239, 1.0
	v_rcp_f32_e32 v241, v240
	v_div_scale_f32 v242, vcc, 1.0, v239, 1.0
	s_nop 0
	v_fma_f32 v243, -v240, v241, 1.0
	v_fmac_f32_e32 v241, v243, v241
	v_mul_f32_e32 v243, v242, v241
	v_fma_f32 v237, -v240, v243, v242
	v_fmac_f32_e32 v243, v237, v241
	v_fma_f32 v240, -v240, v243, v242
	v_div_fmas_f32 v240, v240, v241, v243
	v_div_fixup_f32 v238, v240, v239, 1.0
	v_mul_f32_e32 v0, v0, v238
	v_mul_f32_e32 v1, v1, v238
	v_mul_f32_e32 v2, v2, v238
	v_mul_f32_e32 v3, v3, v238
	v_mul_f32_e32 v4, v4, v238
	v_mul_f32_e32 v5, v5, v238
	v_mul_f32_e32 v6, v6, v238
	v_mul_f32_e32 v7, v7, v238
	v_mul_f32_e32 v8, v8, v238
	v_mul_f32_e32 v9, v9, v238
	v_mul_f32_e32 v10, v10, v238
	v_mul_f32_e32 v11, v11, v238
	v_mul_f32_e32 v12, v12, v238
	v_mul_f32_e32 v13, v13, v238
	v_mul_f32_e32 v14, v14, v238
	v_mul_f32_e32 v15, v15, v238
	v_mul_f32_e32 v16, v16, v238
	v_mul_f32_e32 v17, v17, v238
	v_mul_f32_e32 v18, v18, v238
	v_mul_f32_e32 v19, v19, v238
	v_mul_f32_e32 v20, v20, v238
	v_mul_f32_e32 v21, v21, v238
	v_mul_f32_e32 v22, v22, v238
	v_mul_f32_e32 v23, v23, v238
	v_mul_f32_e32 v24, v24, v238
	v_mul_f32_e32 v25, v25, v238
	v_mul_f32_e32 v26, v26, v238
	v_mul_f32_e32 v27, v27, v238
	v_mul_f32_e32 v28, v28, v238
	v_mul_f32_e32 v29, v29, v238
	v_mul_f32_e32 v30, v30, v238
	v_mul_f32_e32 v31, v31, v238
	s_cmp_gt_u32 s38, 15
	s_cbranch_scc0 .Lc1_noimp
	v_cmp_ne_u32_e64 s[46:47], 0, v101
	ds_bpermute_b32 v32, v193, v176
	ds_bpermute_b32 v33, v193, v177
	ds_bpermute_b32 v34, v193, v178
	ds_bpermute_b32 v35, v193, v179
	ds_bpermute_b32 v36, v193, v180
	ds_bpermute_b32 v37, v193, v181
	ds_bpermute_b32 v38, v193, v182
	ds_bpermute_b32 v39, v193, v183
	ds_bpermute_b32 v40, v193, v246
	ds_bpermute_b32 v41, v193, v247
	ds_bpermute_b32 v42, v193, v248
	ds_bpermute_b32 v43, v193, v249
	ds_bpermute_b32 v44, v193, v250
	ds_bpermute_b32 v45, v193, v251
	ds_bpermute_b32 v46, v193, v252
	ds_bpermute_b32 v47, v193, v253
	v_lshrrev_b32_e32 v48, 7, v152
	v_lshl_or_b32 v48, v48, 6, v98
	v_mul_u32_u24_e32 v48, 0x84, v48
	v_add_u32_e32 v48, v48, v195
	v_add_u32_e32 v48, 0x19e00, v48
	s_waitcnt lgkmcnt(0)
	v_cndmask_b32_e64 v49, 0, v32, s[46:47]
	v_add_f32_e32 v49, v160, v49
	v_mul_f32_e32 v49, v49, v238
	ds_write_b32 v48, v49 offset:0
	v_cndmask_b32_e64 v50, v32, v33, s[46:47]
	v_add_f32_e32 v50, v161, v50
	v_mul_f32_e32 v50, v50, v238
	ds_write_b32 v48, v50 offset:8
	v_cndmask_b32_e64 v49, v33, v34, s[46:47]
	v_add_f32_e32 v49, v162, v49
	v_mul_f32_e32 v49, v49, v238
	ds_write_b32 v48, v49 offset:16
	v_cndmask_b32_e64 v50, v34, v35, s[46:47]
	v_add_f32_e32 v50, v163, v50
	v_mul_f32_e32 v50, v50, v238
	ds_write_b32 v48, v50 offset:24
	v_cndmask_b32_e64 v49, v35, v36, s[46:47]
	v_add_f32_e32 v49, v164, v49
	v_mul_f32_e32 v49, v49, v238
	ds_write_b32 v48, v49 offset:32
	v_cndmask_b32_e64 v50, v36, v37, s[46:47]
	v_add_f32_e32 v50, v165, v50
	v_mul_f32_e32 v50, v50, v238
	ds_write_b32 v48, v50 offset:40
	v_cndmask_b32_e64 v49, v37, v38, s[46:47]
	v_add_f32_e32 v49, v166, v49
	v_mul_f32_e32 v49, v49, v238
	ds_write_b32 v48, v49 offset:48
	v_cndmask_b32_e64 v50, v38, v39, s[46:47]
	v_add_f32_e32 v50, v167, v50
	v_mul_f32_e32 v50, v50, v238
	ds_write_b32 v48, v50 offset:56
	v_cndmask_b32_e64 v49, v39, v40, s[46:47]
	v_add_f32_e32 v49, v168, v49
	v_mul_f32_e32 v49, v49, v238
	ds_write_b32 v48, v49 offset:64
	v_cndmask_b32_e64 v50, v40, v41, s[46:47]
	v_add_f32_e32 v50, v169, v50
	v_mul_f32_e32 v50, v50, v238
	ds_write_b32 v48, v50 offset:72
	v_cndmask_b32_e64 v49, v41, v42, s[46:47]
	v_add_f32_e32 v49, v170, v49
	v_mul_f32_e32 v49, v49, v238
	ds_write_b32 v48, v49 offset:80
	v_cndmask_b32_e64 v50, v42, v43, s[46:47]
	v_add_f32_e32 v50, v171, v50
	v_mul_f32_e32 v50, v50, v238
	ds_write_b32 v48, v50 offset:88
	v_cndmask_b32_e64 v49, v43, v44, s[46:47]
	v_add_f32_e32 v49, v172, v49
	v_mul_f32_e32 v49, v49, v238
	ds_write_b32 v48, v49 offset:96
	v_cndmask_b32_e64 v50, v44, v45, s[46:47]
	v_add_f32_e32 v50, v173, v50
	v_mul_f32_e32 v50, v50, v238
	ds_write_b32 v48, v50 offset:104
	v_cndmask_b32_e64 v49, v45, v46, s[46:47]
	v_add_f32_e32 v49, v174, v49
	v_mul_f32_e32 v49, v49, v238
	ds_write_b32 v48, v49 offset:112
	v_cndmask_b32_e64 v50, v46, v47, s[46:47]
	v_add_f32_e32 v50, v175, v50
	v_mul_f32_e32 v50, v50, v238
	ds_write_b32 v48, v50 offset:120
; #define LAS __attribute__((address_space(3)))
; __device__ __forceinline__ void phase4_attn(const Args& a, LAS unsigned char* lds) {
;     ...
;                     const int qloc = tid >> 3, jg = tid & 7;
;                     unsigned bits = 0u;
;                     float xe[4]; int cnt[4];
; #pragma unroll
;                     for (int e = 0; e < 4; ++e) { const int j = 4 * jg + e; const LAS float* ip = IMP + qloc * A_IMPSTR + j;
;                         float x = (ip[0] + ip[64 * A_IMPSTR]) + (ip[128 * A_IMPSTR] + ip[192 * A_IMPSTR]);
;                         if (j == 0 || j == t || j == t - 1) x = 1e9f;
;                         if (j > t) x = -INFINITY;
;                         xe[e] = x; cnt[e] = 0; }
; #pragma unroll 4
;                     for (int i = 0; i < 32; ++i) { const LAS float* ip = IMP + qloc * A_IMPSTR + i;
;                         float vi = (ip[0] + ip[64 * A_IMPSTR]) + (ip[128 * A_IMPSTR] + ip[192 * A_IMPSTR]);
;                         if (i == 0 || i == t || i == t - 1) vi = 1e9f;
;                         if (i > t) vi = -INFINITY;
; #pragma unroll
;                         for (int e = 0; e < 4; ++e) cnt[e] += (vi > xe[e] || (vi == xe[e] && i < 4 * jg + e)) ? 1 : 0; }
; #pragma unroll
;                     for (int e = 0; e < 4; ++e) if (cnt[e] < 16 && xe[e] > -INFINITY) bits |= 1u << (4 * jg + e);
;     ...
;                 for (int ks = 0; ks < 4; ++ks) qf[ks] = __builtin_nontemporal_load((const bf16x8_t*)(qr + (size_t)tok * 512 + head * 64 + 16 * ks + 8 * h));
;                 const int kt_lo = t >= 8 ? t - 8 : 0, wlo = kt_lo >> 1, n_sel = (t >> 1) + 1, n_all = n_sel + ((t >> 1) - wlo + 1);
;                 const bf16_t* Ks = ksl + (size_t)bh * 2048 * 64; const bf16_t* Vs = vslT + (size_t)bh * 64 * 2048;
;                 const bf16_t* Kw = kwn + (size_t)bh * 2048 * 64; const bf16_t* Vw = vwnT + (size_t)bh * 64 * 2048;
.Lc1_noimp:
	s_waitcnt lgkmcnt(0)
	v_readlane_b32 s10, v254, 61
	v_readlane_b32 s11, v254, 62
	v_lshlrev_b32_e32 v200, 1, v196
	v_mov_b32_e32 v201, 0
	v_lshl_add_u64 v[202:203], s[10:11], 0, v[72:73]
	v_lshl_add_u64 v[202:203], v[202:203], 0, v[200:201]
	global_load_dwordx4 v[80:83], v[202:203], off nt
	global_load_dwordx4 v[84:87], v[202:203], off offset:32 nt
	global_load_dwordx4 v[88:91], v[202:203], off offset:64 nt
	global_load_dwordx4 v[92:95], v[202:203], off offset:96 nt
	v_mov_b32_e32 v200, v152
	v_lshlrev_b64 v[200:201], 4, v[200:201]
	v_lshl_add_u64 v[206:207], v[200:201], 0, s[40:41]
	v_lshl_add_u64 v[204:205], s[54:55], 0, v[200:201]
	global_load_dwordx4 v[208:211], v[204:205], off
	v_lshl_add_u64 v[204:205], s[54:55], 0, v[206:207]
	global_load_dwordx4 v[212:215], v[204:205], off
	v_lshl_add_u64 v[204:205], s[56:57], 0, v[200:201]
	global_load_dwordx4 v[104:107], v[204:205], off
	v_lshl_add_u64 v[204:205], s[56:57], 0, v[206:207]
	global_load_dwordx4 v[108:111], v[204:205], off
	v_mov_b32_e32 v198, s30
	s_and_b64 vcc, exec, s[2:3]
	s_cbranch_vccnz .LBB0_804
	s_movk_i32 s0, 0x84
	v_mul_lo_u32 v50, v99, s0
	v_readlane_b32 s0, v254, 28
	v_and_b32_e32 v33, 7, v152
	s_nop 0
	v_add_u32_e32 v46, s0, v50
	v_lshl_add_u32 v32, v33, 4, v46
	v_add_u32_e32 v40, 0x2100, v32
	v_add_u32_e32 v36, 0x4200, v32
	v_add_u32_e32 v38, 0x6300, v32
	s_barrier
	ds_read2_b32 v[34:35], v32 offset1:1
	ds_read2_b32 v[36:37], v36 offset1:1
	ds_read2_b32 v[38:39], v38 offset1:1
	ds_read2_b32 v[40:41], v40 offset1:1
	v_lshlrev_b32_e32 v32, 2, v33
	s_waitcnt lgkmcnt(3)
	v_mov_b32_e32 v42, v34
	s_waitcnt lgkmcnt(2)
	v_mov_b32_e32 v43, v36
	s_waitcnt lgkmcnt(1)
	v_mov_b32_e32 v45, v38
	s_waitcnt lgkmcnt(0)
	v_mov_b32_e32 v44, v40
	v_cmp_eq_u32_e32 vcc, 0, v33
	v_cmp_eq_u32_e64 s[0:1], s38, v32
	v_pk_add_f32 v[42:43], v[42:43], v[44:45]
	s_or_b64 s[2:3], vcc, s[0:1]
	v_cmp_eq_u32_e64 s[0:1], s80, v32
	v_add_f32_e32 v34, v42, v43
	s_or_b64 s[0:1], s[2:3], s[0:1]
	v_cndmask_b32_e64 v33, v34, v190, s[0:1]
	v_cmp_ge_u32_e64 s[0:1], s38, v32
	v_mov_b32_e32 v36, v35
	v_mov_b32_e32 v38, v41
	v_cndmask_b32_e64 v34, v191, v33, s[0:1]
	v_or_b32_e32 v33, 1, v32
	v_pk_add_f32 v[36:37], v[36:37], v[38:39]
	v_cmp_eq_u32_e64 s[0:1], s38, v33
	v_cmp_eq_u32_e64 s[2:3], s80, v33
	v_add_f32_e32 v35, v36, v37
	s_or_b64 s[0:1], s[0:1], s[2:3]
	v_or_b32_e32 v38, 2, v32
	v_cndmask_b32_e64 v33, v35, v190, s[0:1]
	v_lshl_add_u32 v35, v38, 2, v46
	v_add_u32_e32 v36, 0x2100, v35
	v_add_u32_e32 v37, 0x4200, v35
	v_add_u32_e32 v39, 0x6300, v35
	ds_read2_b32 v[40:41], v35 offset1:1
	ds_read2_b32 v[44:45], v36 offset1:1
	ds_read2_b32 v[46:47], v37 offset1:1
	ds_read2_b32 v[48:49], v39 offset1:1
	v_cmp_gt_u32_e64 s[0:1], s38, v32
	v_or_b32_e32 v42, 3, v32
	s_waitcnt lgkmcnt(2)
	v_pk_add_f32 v[40:41], v[40:41], v[44:45]
	v_cndmask_b32_e64 v36, v191, v33, s[0:1]
	s_waitcnt lgkmcnt(0)
	v_pk_add_f32 v[44:45], v[46:47], v[48:49]
	v_cmp_eq_u32_e64 s[0:1], s38, v38
	v_cmp_eq_u32_e64 s[4:5], s80, v38
	v_pk_add_f32 v[40:41], v[40:41], v[44:45]
	v_cmp_eq_u32_e64 s[2:3], s38, v42
	v_cmp_eq_u32_e64 s[6:7], s80, v42
	s_or_b64 s[0:1], s[0:1], s[4:5]
	v_cndmask_b32_e64 v37, v40, v190, s[0:1]
	s_or_b64 s[0:1], s[2:3], s[6:7]
	v_cndmask_b32_e64 v33, v41, v190, s[0:1]
	v_cmp_ge_u32_e64 s[0:1], s38, v42
	s_mov_b32 s30, 0
	s_mov_b32 s42, 1
	v_cndmask_b32_e64 v33, v191, v33, s[0:1]
	v_cmp_ge_u32_e64 s[0:1], s38, v38
	v_mov_b32_e32 v35, v32
	s_mov_b32 s43, s38
	v_cndmask_b32_e64 v40, v191, v37, s[0:1]
	s_mov_b32 s44, s80
	v_mov_b32_e32 v37, v34
	v_mov_b32_e32 v39, v36
	v_mov_b32_e32 v41, v38
	v_mov_b32_e32 v44, v40
	v_mov_b32_e32 v43, v40
	v_mov_b32_e32 v45, v42
	v_mov_b32_e32 v46, v33
	v_mov_b32_e32 v47, v33
	v_add_u32_e32 v48, 0, v50
	v_mov_b32_e32 v49, 0
	v_mov_b32_e32 v50, 0
	v_mov_b32_e32 v51, 0
	v_mov_b32_e32 v52, 0
	v_mov_b32_e32 v53, 0
	v_mov_b32_e32 v54, 0
	v_mov_b32_e32 v55, 0
	v_mov_b32_e32 v56, 0
	s_mov_b32 s45, 0

; __device__ __forceinline__ void phase4_attn(const Args& a, LAS unsigned char* lds) {
;     ...
;                     comb[hkv][0] += oc[0] * g0; comb[hkv][1] += oc[1] * g0;
;     ...
;                 const int kt_lo = t >= 8 ? t - 8 : 0, wlo = kt_lo >> 1, n_sel = (t >> 1) + 1, n_all = n_sel + ((t >> 1) - wlo + 1);
;                 const bf16_t* Ks = ksl + (size_t)bh * 2048 * 64; const bf16_t* Vs = vslT + (size_t)bh * 64 * 2048;
;                 const bf16_t* Kw = kwn + (size_t)bh * 2048 * 64; const bf16_t* Vw = vwnT + (size_t)bh * 64 * 2048;
;     ...
;                 u32x4 kR0, kR1, vR0, vR1;
;                 A_ISSUE(0);
;                 A_STAGE(0);
;                 __syncthreads();
;                 f32x16 oacc[2]; oacc[0] = zero16(); oacc[1] = zero16();
.LBB0_804:
	v_pk_fma_f32 v[182:183], v[112:113], v[0:1], 0 op_sel_hi:[0,1,0]
	v_mov_b32_e32 v0, v152
	v_pk_fma_f32 v[186:187], v[112:113], v[2:3], 0 op_sel_hi:[0,1,0]
	v_ashrrev_i32_e32 v1, 3, v0
	v_lshlrev_b32_e32 v0, 4, v0
	v_mul_lo_u32 v2, v1, s87
	v_and_b32_e32 v0, 0x70, v0
	v_add3_u32 v0, 0, v2, v0
	v_pk_fma_f32 v[166:167], v[112:113], v[14:15], 0 op_sel_hi:[0,1,0]
	v_pk_fma_f32 v[172:173], v[112:113], v[12:13], 0 op_sel_hi:[0,1,0]
	v_pk_fma_f32 v[174:175], v[112:113], v[10:11], 0 op_sel_hi:[0,1,0]
	v_pk_fma_f32 v[176:177], v[112:113], v[8:9], 0 op_sel_hi:[0,1,0]
	v_pk_fma_f32 v[178:179], v[112:113], v[6:7], 0 op_sel_hi:[0,1,0]
	v_pk_fma_f32 v[180:181], v[112:113], v[4:5], 0 op_sel_hi:[0,1,0]
	v_pk_fma_f32 v[168:169], v[112:113], v[16:17], 0 op_sel_hi:[0,1,0]
	v_pk_fma_f32 v[154:155], v[112:113], v[30:31], 0 op_sel_hi:[0,1,0]
	v_pk_fma_f32 v[156:157], v[112:113], v[28:29], 0 op_sel_hi:[0,1,0]
	v_pk_fma_f32 v[158:159], v[112:113], v[26:27], 0 op_sel_hi:[0,1,0]
	v_pk_fma_f32 v[160:161], v[112:113], v[24:25], 0 op_sel_hi:[0,1,0]
	v_pk_fma_f32 v[162:163], v[112:113], v[22:23], 0 op_sel_hi:[0,1,0]
	v_pk_fma_f32 v[164:165], v[112:113], v[20:21], 0 op_sel_hi:[0,1,0]
	v_pk_fma_f32 v[170:171], v[112:113], v[18:19], 0 op_sel_hi:[0,1,0]
	s_andn2_b64 vcc, exec, s[64:65]
	v_mad_u64_u32 v[2:3], s[0:1], v1, s35, v[0:1]
	v_add_u32_e32 v1, 0x9000, v2
	v_add_u32_e32 v2, 0x9080, v2
	s_waitcnt vmcnt(3)
	ds_write_b128 v0, v[208:211]
	s_waitcnt vmcnt(2)
	ds_write_b128 v0, v[212:215] offset:9216
	s_waitcnt vmcnt(1)
	ds_write2_b64 v1, v[104:105], v[106:107] offset1:1
	s_waitcnt vmcnt(0)
	ds_write2_b64 v2, v[108:109], v[110:111] offset1:1
	s_waitcnt lgkmcnt(0)
	s_barrier
	s_cbranch_vccnz .LBB0_873
	s_lshl_b32 s0, s89, 1
	s_sub_i32 s30, s0, s31
	s_lshl_b32 s1, s31, 1
	v_mov_b32_e32 v112, 0
	s_mov_b32 s10, 1
	s_add_i32 s11, s30, 1
	s_add_i32 s30, s30, 2
	s_sub_i32 s31, s1, s0
	s_mov_b32 s44, 0
	v_mov_b32_e32 v0, 0
	v_mov_b32_e32 v1, v112
	v_mov_b32_e32 v2, v112
	v_mov_b32_e32 v3, v112
	v_mov_b32_e32 v4, v112
	v_mov_b32_e32 v5, v112
	v_mov_b32_e32 v6, v112
	v_mov_b32_e32 v7, v112
	v_mov_b32_e32 v8, v112
	v_mov_b32_e32 v9, v112
	v_mov_b32_e32 v10, v112
	v_mov_b32_e32 v11, v112
	v_mov_b32_e32 v12, v112
	v_mov_b32_e32 v13, v112
	v_mov_b32_e32 v14, v112
	v_mov_b32_e32 v15, v112
	v_mov_b32_e32 v16, 0
	v_mov_b32_e32 v17, v112
	v_mov_b32_e32 v18, v112
	v_mov_b32_e32 v19, v112
	v_mov_b32_e32 v20, v112
	v_mov_b32_e32 v21, v112
	v_mov_b32_e32 v22, v112
	v_mov_b32_e32 v23, v112
	v_mov_b32_e32 v24, v112
	v_mov_b32_e32 v25, v112
	v_mov_b32_e32 v26, v112
	v_mov_b32_e32 v27, v112
	v_mov_b32_e32 v28, v112
	v_mov_b32_e32 v29, v112
	v_mov_b32_e32 v30, v112
	v_mov_b32_e32 v31, v112
